# P6 row scales precomputed once per WG into LDS (no global loads or vmcnt(0) in its epilogue); P1 unit-start vmcnt(0) removed; attention epilogue z loads hoisted
# speedup vs baseline: 1.0205x; 1.0118x over previous
; template <class Epi, class Sched>
; __device__ __forceinline__ void gemm_phase(LAS unsigned char* lds, const Gemm g, const Sched& S, const Epi& E) {
;     ...
;         const bool has_next = S.next(ui + 1, nxt);
;         const char* nA = has_next ? (const char*)g.A + (size_t)nxt.pm * tsA : cA; const char* nB = has_next ? (const char*)g.Bt + (size_t)nxt.pn * tsB : cB;
;     ...
; #pragma unroll
;         for (int a = 0; a < 2; ++a)
; #pragma unroll
;             for (int b = 0; b < 2; ++b)
; #pragma unroll
;                 for (int m = 0; m < 4; ++m)
; #pragma unroll
;                     for (int n = 0; n < 2; ++n) acc[a][b][m][n] = (f32x4){0.f, 0.f, 0.f, 0.f};
.LBB0_239:
	s_ashr_i32 s1, s0, 31
	s_lshl_b64 s[42:43], s[0:1], 20
	s_add_u32 s42, s53, s42
	s_addc_u32 s43, s54, s43
	s_and_b64 s[44:45], s[6:7], exec
	s_cselect_b32 s1, s43, s9
	s_cselect_b32 s11, s42, s8
	s_ashr_i32 s41, s40, 31
	s_lshl_b64 s[44:45], s[40:41], 20
	s_add_u32 s44, s55, s44
	s_addc_u32 s45, s64, s45
	s_and_b64 s[48:49], s[6:7], exec
	s_cselect_b32 s22, s45, s47
	s_cselect_b32 s41, s44, s46
	s_add_u32 s8, s8, 0x80080
	s_addc_u32 s9, s9, 0
	s_add_u32 s50, s46, 0x100
	v_mov_b32_e32 v0, 0
	s_addc_u32 s51, s47, 0
	s_mov_b32 vcc_lo, -2
	v_mov_b32_e32 v1, v0
	v_mov_b32_e32 v2, v0
	v_mov_b32_e32 v3, v0
	v_mov_b32_e32 v4, v0
	v_mov_b32_e32 v5, v0
	v_mov_b32_e32 v6, v0
	v_mov_b32_e32 v7, v0
	v_mov_b32_e32 v16, v0
	v_mov_b32_e32 v17, v0
	v_mov_b32_e32 v18, v0
	v_mov_b32_e32 v19, v0
	v_mov_b32_e32 v20, v0
	v_mov_b32_e32 v21, v0
	v_mov_b32_e32 v22, v0
	v_mov_b32_e32 v23, v0
	v_mov_b32_e32 v32, v0
	v_mov_b32_e32 v33, v0
	v_mov_b32_e32 v34, v0
	v_mov_b32_e32 v35, v0
	v_mov_b32_e32 v36, v0
	v_mov_b32_e32 v37, v0
	v_mov_b32_e32 v38, v0
	v_mov_b32_e32 v39, v0
	v_mov_b32_e32 v48, v0
	v_mov_b32_e32 v49, v0
	v_mov_b32_e32 v50, v0
	v_mov_b32_e32 v51, v0
	v_mov_b32_e32 v52, v0
	v_mov_b32_e32 v53, v0
	v_mov_b32_e32 v54, v0
	v_mov_b32_e32 v55, v0
	v_mov_b32_e32 v8, v0
	v_mov_b32_e32 v9, v0
	v_mov_b32_e32 v10, v0
	v_mov_b32_e32 v11, v0
	v_mov_b32_e32 v12, v0
	v_mov_b32_e32 v13, v0
	v_mov_b32_e32 v14, v0
	v_mov_b32_e32 v15, v0
	v_mov_b32_e32 v24, v0
	v_mov_b32_e32 v25, v0
	v_mov_b32_e32 v26, v0
	v_mov_b32_e32 v27, v0
	v_mov_b32_e32 v28, v0
	v_mov_b32_e32 v29, v0
	v_mov_b32_e32 v30, v0
	v_mov_b32_e32 v31, v0
	v_mov_b32_e32 v40, v0
	v_mov_b32_e32 v41, v0
	v_mov_b32_e32 v42, v0
	v_mov_b32_e32 v43, v0
	v_mov_b32_e32 v44, v0
	v_mov_b32_e32 v45, v0
	v_mov_b32_e32 v46, v0
	v_mov_b32_e32 v47, v0
	v_mov_b32_e32 v56, v0
	v_mov_b32_e32 v57, v0
	v_mov_b32_e32 v58, v0
	v_mov_b32_e32 v59, v0
	s_nop 0
	v_mov_b32_e32 v68, v0
	v_mov_b32_e32 v69, v0
	v_mov_b32_e32 v70, v0
	v_mov_b32_e32 v71, v0
	v_mov_b32_e32 v72, v0
	v_mov_b32_e32 v73, v0
	v_mov_b32_e32 v74, v0
	v_mov_b32_e32 v75, v0
	v_mov_b32_e32 v76, v0
	v_mov_b32_e32 v77, v0
	v_mov_b32_e32 v78, v0
	v_mov_b32_e32 v79, v0
	v_mov_b32_e32 v96, v0
	v_mov_b32_e32 v97, v0
	v_mov_b32_e32 v98, v0
	v_mov_b32_e32 v99, v0
	v_mov_b32_e32 v100, v0
	v_mov_b32_e32 v101, v0
	v_mov_b32_e32 v102, v0
	v_mov_b32_e32 v103, v0
	v_mov_b32_e32 v120, v0
	v_mov_b32_e32 v121, v0
	v_mov_b32_e32 v122, v0
	v_mov_b32_e32 v123, v0
	v_mov_b32_e32 v124, v0
	v_mov_b32_e32 v125, v0
	v_mov_b32_e32 v126, v0
	v_mov_b32_e32 v127, v0
	v_mov_b32_e32 v144, v0
	v_mov_b32_e32 v145, v0
	v_mov_b32_e32 v146, v0
	v_mov_b32_e32 v147, v0
	v_mov_b32_e32 v148, v0
	v_mov_b32_e32 v149, v0
	v_mov_b32_e32 v150, v0
	v_mov_b32_e32 v151, v0
	v_mov_b32_e32 v84, v0
	v_mov_b32_e32 v85, v0
	v_mov_b32_e32 v86, v0
	v_mov_b32_e32 v87, v0
	v_mov_b32_e32 v88, v0
	v_mov_b32_e32 v89, v0
	v_mov_b32_e32 v90, v0
	v_mov_b32_e32 v91, v0
	v_mov_b32_e32 v108, v0
	v_mov_b32_e32 v109, v0
	v_mov_b32_e32 v110, v0
	v_mov_b32_e32 v111, v0
	v_mov_b32_e32 v116, v0
	v_mov_b32_e32 v117, v0
	v_mov_b32_e32 v118, v0
	v_mov_b32_e32 v119, v0
	v_mov_b32_e32 v136, v0
	v_mov_b32_e32 v137, v0
	v_mov_b32_e32 v138, v0
	v_mov_b32_e32 v139, v0
	v_mov_b32_e32 v140, v0
	v_mov_b32_e32 v141, v0
	v_mov_b32_e32 v142, v0
	v_mov_b32_e32 v143, v0
	v_mov_b32_e32 v160, v0
	v_mov_b32_e32 v161, v0
	v_mov_b32_e32 v162, v0
	v_mov_b32_e32 v163, v0
	v_mov_b32_e32 v164, v0
	v_mov_b32_e32 v165, v0
	v_mov_b32_e32 v166, v0
	v_mov_b32_e32 v167, v0

; #define LAS __attribute__((address_space(3)))
; DI float siluf_(float x) { return x * frcp(1.f + fexp(-x)); }
; DI u32x4 pack8(const f32x4 a, const f32x4 b) { u32x4 w; w.x = pk2(a[0], a[1]); w.y = pk2(a[2], a[3]); w.z = pk2(b[0], b[1]); w.w = pk2(b[2], b[3]); return w; }
; DI void attn_item(LAS unsigned char* lds, int bh, int qb, const bf16_t* QH, const bf16_t* KN, const bf16_t* KPE, const bf16_t* VT, const bf16_t* P, bf16_t* MIX) {
;     ...
;     __syncthreads();
;     {
;         const bf16_t* zp = P + ((size_t)b * SEQ + q0) * LDP + 4160 + h * 128;
;         bf16_t* op = MIX + ((size_t)b * SEQ + q0) * DM + 1024 + h * 128;
; #pragma nounroll
;         for (int j = 0; j < 4; ++j) {
;             const int id = tid + 512 * j, q = id >> 4, c8 = (id & 15) * 8;
;             const u32x4 ov = *(const LAS u32x4*)(OBa + q * 272 + c8 * 2);
;             const u32x4 z = *(const u32x4*)(zp + (size_t)q * LDP + c8);
;             f32x4 o0, o1;
;             o0[0] = bflo(ov.x) * siluf_(bflo(z.x)); o0[1] = bfhi(ov.x) * siluf_(bfhi(z.x)); o0[2] = bflo(ov.y) * siluf_(bflo(z.y)); o0[3] = bfhi(ov.y) * siluf_(bfhi(z.y));
;             o1[0] = bflo(ov.z) * siluf_(bflo(z.z)); o1[1] = bfhi(ov.z) * siluf_(bfhi(z.z)); o1[2] = bflo(ov.w) * siluf_(bflo(z.w)); o1[3] = bfhi(ov.w) * siluf_(bfhi(z.w));
;             *(u32x4*)(op + (size_t)q * DM + c8) = pack8(o0, o1);
;         }
.LBB0_606:
	s_lshl_b64 s[22:23], s[20:21], 24
	s_lshl_b32 s21, s35, 19
	s_lshl_b32 s36, s52, 4
	s_or_b32 s21, s22, s21
	s_and_b32 s36, s36, 0x700
	s_or_b32 s38, s21, s36
	s_mov_b32 s39, s23
	v_lshl_add_u64 v[0:1], v[178:179], 0, s[38:39]
	s_mul_i32 s38, s20, 0x2880000
	s_mul_i32 s35, s35, 0x144000
	s_mul_hi_i32 s37, s20, 0x2880000
	s_add_u32 s20, s38, s35
	s_addc_u32 s21, s37, 0
	s_or_b32 s20, s20, s36
	v_lshl_add_u64 v[2:3], v[180:181], 0, s[20:21]
	s_mov_b32 s20, 0xffff7800
	global_load_dwordx4 v[28:31], v[2:3], off
	v_lshl_add_u64 v[2:3], v[2:3], 0, s[16:17]
	global_load_dwordx4 v[32:35], v[2:3], off
	v_lshl_add_u64 v[2:3], v[2:3], 0, s[16:17]
	global_load_dwordx4 v[36:39], v[2:3], off
	v_lshl_add_u64 v[2:3], v[2:3], 0, s[16:17]
	global_load_dwordx4 v[40:43], v[2:3], off
	s_waitcnt lgkmcnt(0)
	s_barrier
	v_add_u32_e32 v8, s20, v228
	ds_read_b128 v[8:11], v8 offset:34816
	s_addk_i32 s20, 0x2200
	s_waitcnt lgkmcnt(0)
	v_lshlrev_b32_e32 v12, 16, v8
	v_and_b32_e32 v13, 0xffff0000, v8
	v_lshlrev_b32_e32 v8, 16, v9
	v_and_b32_e32 v9, 0xffff0000, v9
	v_lshlrev_b32_e32 v14, 16, v10
	v_and_b32_e32 v15, 0xffff0000, v10
	v_lshlrev_b32_e32 v10, 16, v11
	v_and_b32_e32 v11, 0xffff0000, v11
	s_waitcnt vmcnt(3)
	v_mov_b32_e32 v4, v28
	v_mov_b32_e32 v5, v29
	v_mov_b32_e32 v6, v30
	v_mov_b32_e32 v7, v31
	v_lshlrev_b32_e32 v16, 16, v4
	v_and_b32_e32 v17, 0xffff0000, v4
	v_lshlrev_b32_e32 v4, 16, v5
	v_and_b32_e32 v5, 0xffff0000, v5
	v_lshlrev_b32_e32 v18, 16, v6
	v_and_b32_e32 v19, 0xffff0000, v6
	v_lshlrev_b32_e32 v6, 16, v7
	v_and_b32_e32 v7, 0xffff0000, v7
	v_mul_f32_e32 v20, 0xbfb8aa3b, v16
	v_mul_f32_e32 v21, 0xbfb8aa3b, v17
	v_mul_f32_e32 v22, 0xbfb8aa3b, v4
	v_mul_f32_e32 v23, 0xbfb8aa3b, v5
	v_mul_f32_e32 v24, 0xbfb8aa3b, v18
	v_mul_f32_e32 v25, 0xbfb8aa3b, v19
	v_mul_f32_e32 v26, 0xbfb8aa3b, v6
	v_mul_f32_e32 v27, 0xbfb8aa3b, v7
	v_exp_f32_e32 v20, v20
	v_exp_f32_e32 v21, v21
	v_exp_f32_e32 v22, v22
	v_exp_f32_e32 v23, v23
	v_exp_f32_e32 v24, v24
	v_exp_f32_e32 v25, v25
	v_exp_f32_e32 v26, v26
	v_exp_f32_e32 v27, v27
	v_add_f32_e32 v20, 1.0, v20
	v_add_f32_e32 v21, 1.0, v21
	v_add_f32_e32 v22, 1.0, v22
	v_add_f32_e32 v23, 1.0, v23
	v_add_f32_e32 v24, 1.0, v24
	v_add_f32_e32 v25, 1.0, v25
	v_add_f32_e32 v26, 1.0, v26
	v_add_f32_e32 v27, 1.0, v27
	v_rcp_f32_e32 v20, v20
	v_rcp_f32_e32 v21, v21
	v_rcp_f32_e32 v22, v22
	v_rcp_f32_e32 v23, v23
	v_rcp_f32_e32 v24, v24
	v_rcp_f32_e32 v25, v25
	v_rcp_f32_e32 v26, v26
	v_rcp_f32_e32 v27, v27
	v_pk_mul_f32 v[16:17], v[20:21], v[16:17]
	v_pk_mul_f32 v[4:5], v[22:23], v[4:5]
	v_pk_mul_f32 v[18:19], v[24:25], v[18:19]
	v_pk_mul_f32 v[6:7], v[26:27], v[6:7]
	v_pk_mul_f32 v[12:13], v[16:17], v[12:13]
	v_pk_mul_f32 v[8:9], v[4:5], v[8:9]
	v_pk_mul_f32 v[14:15], v[18:19], v[14:15]
	v_pk_mul_f32 v[10:11], v[6:7], v[10:11]
	v_cvt_pk_bf16_f32 v4, v12, v13
	v_cvt_pk_bf16_f32 v5, v8, v9
	v_cvt_pk_bf16_f32 v6, v14, v15
	v_cvt_pk_bf16_f32 v7, v10, v11
	global_store_dwordx4 v[0:1], v[4:7], off
	v_lshl_add_u64 v[0:1], v[0:1], 0, s[12:13]
	v_add_u32_e32 v8, s20, v228
	ds_read_b128 v[8:11], v8 offset:34816
	s_addk_i32 s20, 0x2200
	s_waitcnt lgkmcnt(0)
	v_lshlrev_b32_e32 v12, 16, v8
	v_and_b32_e32 v13, 0xffff0000, v8
	v_lshlrev_b32_e32 v8, 16, v9
	v_and_b32_e32 v9, 0xffff0000, v9
	v_lshlrev_b32_e32 v14, 16, v10
	v_and_b32_e32 v15, 0xffff0000, v10
	v_lshlrev_b32_e32 v10, 16, v11
	v_and_b32_e32 v11, 0xffff0000, v11
	s_waitcnt vmcnt(3)
	v_mov_b32_e32 v4, v32
	v_mov_b32_e32 v5, v33
	v_mov_b32_e32 v6, v34
	v_mov_b32_e32 v7, v35
	v_lshlrev_b32_e32 v16, 16, v4
	v_and_b32_e32 v17, 0xffff0000, v4
	v_lshlrev_b32_e32 v4, 16, v5
	v_and_b32_e32 v5, 0xffff0000, v5
	v_lshlrev_b32_e32 v18, 16, v6
	v_and_b32_e32 v19, 0xffff0000, v6
	v_lshlrev_b32_e32 v6, 16, v7
	v_and_b32_e32 v7, 0xffff0000, v7
	v_mul_f32_e32 v20, 0xbfb8aa3b, v16
	v_mul_f32_e32 v21, 0xbfb8aa3b, v17
	v_mul_f32_e32 v22, 0xbfb8aa3b, v4
	v_mul_f32_e32 v23, 0xbfb8aa3b, v5
	v_mul_f32_e32 v24, 0xbfb8aa3b, v18
	v_mul_f32_e32 v25, 0xbfb8aa3b, v19
	v_mul_f32_e32 v26, 0xbfb8aa3b, v6
	v_mul_f32_e32 v27, 0xbfb8aa3b, v7
	v_exp_f32_e32 v20, v20
	v_exp_f32_e32 v21, v21
	v_exp_f32_e32 v22, v22
	v_exp_f32_e32 v23, v23
	v_exp_f32_e32 v24, v24
	v_exp_f32_e32 v25, v25
	v_exp_f32_e32 v26, v26
	v_exp_f32_e32 v27, v27
	v_add_f32_e32 v20, 1.0, v20
	v_add_f32_e32 v21, 1.0, v21
	v_add_f32_e32 v22, 1.0, v22
	v_add_f32_e32 v23, 1.0, v23
	v_add_f32_e32 v24, 1.0, v24
	v_add_f32_e32 v25, 1.0, v25
	v_add_f32_e32 v26, 1.0, v26
	v_add_f32_e32 v27, 1.0, v27
	v_rcp_f32_e32 v20, v20
	v_rcp_f32_e32 v21, v21
	v_rcp_f32_e32 v22, v22
	v_rcp_f32_e32 v23, v23
	v_rcp_f32_e32 v24, v24
	v_rcp_f32_e32 v25, v25
	v_rcp_f32_e32 v26, v26
	v_rcp_f32_e32 v27, v27
	v_pk_mul_f32 v[16:17], v[20:21], v[16:17]
	v_pk_mul_f32 v[4:5], v[22:23], v[4:5]
	v_pk_mul_f32 v[18:19], v[24:25], v[18:19]
	v_pk_mul_f32 v[6:7], v[26:27], v[6:7]
	v_pk_mul_f32 v[12:13], v[16:17], v[12:13]
	v_pk_mul_f32 v[8:9], v[4:5], v[8:9]
	v_pk_mul_f32 v[14:15], v[18:19], v[14:15]
	v_pk_mul_f32 v[10:11], v[6:7], v[10:11]
	v_cvt_pk_bf16_f32 v4, v12, v13
	v_cvt_pk_bf16_f32 v5, v8, v9
	v_cvt_pk_bf16_f32 v6, v14, v15
	v_cvt_pk_bf16_f32 v7, v10, v11
	global_store_dwordx4 v[0:1], v[4:7], off
	v_lshl_add_u64 v[0:1], v[0:1], 0, s[12:13]
	v_add_u32_e32 v8, s20, v228
	ds_read_b128 v[8:11], v8 offset:34816
	s_addk_i32 s20, 0x2200
	s_waitcnt lgkmcnt(0)
	v_lshlrev_b32_e32 v12, 16, v8
	v_and_b32_e32 v13, 0xffff0000, v8
	v_lshlrev_b32_e32 v8, 16, v9
	v_and_b32_e32 v9, 0xffff0000, v9
	v_lshlrev_b32_e32 v14, 16, v10
	v_and_b32_e32 v15, 0xffff0000, v10
	v_lshlrev_b32_e32 v10, 16, v11
	v_and_b32_e32 v11, 0xffff0000, v11
	s_waitcnt vmcnt(3)
; #define LAS __attribute__((address_space(3)))
; DI float siluf_(float x) { return x * frcp(1.f + fexp(-x)); }
; DI u32x4 pack8(const f32x4 a, const f32x4 b) { u32x4 w; w.x = pk2(a[0], a[1]); w.y = pk2(a[2], a[3]); w.z = pk2(b[0], b[1]); w.w = pk2(b[2], b[3]); return w; }
; DI void attn_item(LAS unsigned char* lds, int bh, int qb, const bf16_t* QH, const bf16_t* KN, const bf16_t* KPE, const bf16_t* VT, const bf16_t* P, bf16_t* MIX) {
;     ...
;         for (int j = 0; j < 4; ++j) {
;             const int id = tid + 512 * j, q = id >> 4, c8 = (id & 15) * 8;
;             const u32x4 ov = *(const LAS u32x4*)(OBa + q * 272 + c8 * 2);
;             const u32x4 z = *(const u32x4*)(zp + (size_t)q * LDP + c8);
;             f32x4 o0, o1;
;             o0[0] = bflo(ov.x) * siluf_(bflo(z.x)); o0[1] = bfhi(ov.x) * siluf_(bfhi(z.x)); o0[2] = bflo(ov.y) * siluf_(bflo(z.y)); o0[3] = bfhi(ov.y) * siluf_(bfhi(z.y));
;             o1[0] = bflo(ov.z) * siluf_(bflo(z.z)); o1[1] = bfhi(ov.z) * siluf_(bfhi(z.z)); o1[2] = bflo(ov.w) * siluf_(bflo(z.w)); o1[3] = bfhi(ov.w) * siluf_(bfhi(z.w));
;             *(u32x4*)(op + (size_t)q * DM + c8) = pack8(o0, o1);
;         }
;     }
;     __syncthreads();
	v_mov_b32_e32 v4, v36
	v_mov_b32_e32 v5, v37
	v_mov_b32_e32 v6, v38
	v_mov_b32_e32 v7, v39
	v_lshlrev_b32_e32 v16, 16, v4
	v_and_b32_e32 v17, 0xffff0000, v4
	v_lshlrev_b32_e32 v4, 16, v5
	v_and_b32_e32 v5, 0xffff0000, v5
	v_lshlrev_b32_e32 v18, 16, v6
	v_and_b32_e32 v19, 0xffff0000, v6
	v_lshlrev_b32_e32 v6, 16, v7
	v_and_b32_e32 v7, 0xffff0000, v7
	v_mul_f32_e32 v20, 0xbfb8aa3b, v16
	v_mul_f32_e32 v21, 0xbfb8aa3b, v17
	v_mul_f32_e32 v22, 0xbfb8aa3b, v4
	v_mul_f32_e32 v23, 0xbfb8aa3b, v5
	v_mul_f32_e32 v24, 0xbfb8aa3b, v18
	v_mul_f32_e32 v25, 0xbfb8aa3b, v19
	v_mul_f32_e32 v26, 0xbfb8aa3b, v6
	v_mul_f32_e32 v27, 0xbfb8aa3b, v7
	v_exp_f32_e32 v20, v20
	v_exp_f32_e32 v21, v21
	v_exp_f32_e32 v22, v22
	v_exp_f32_e32 v23, v23
	v_exp_f32_e32 v24, v24
	v_exp_f32_e32 v25, v25
	v_exp_f32_e32 v26, v26
	v_exp_f32_e32 v27, v27
	v_add_f32_e32 v20, 1.0, v20
	v_add_f32_e32 v21, 1.0, v21
	v_add_f32_e32 v22, 1.0, v22
	v_add_f32_e32 v23, 1.0, v23
	v_add_f32_e32 v24, 1.0, v24
	v_add_f32_e32 v25, 1.0, v25
	v_add_f32_e32 v26, 1.0, v26
	v_add_f32_e32 v27, 1.0, v27
	v_rcp_f32_e32 v20, v20
	v_rcp_f32_e32 v21, v21
	v_rcp_f32_e32 v22, v22
	v_rcp_f32_e32 v23, v23
	v_rcp_f32_e32 v24, v24
	v_rcp_f32_e32 v25, v25
	v_rcp_f32_e32 v26, v26
	v_rcp_f32_e32 v27, v27
	v_pk_mul_f32 v[16:17], v[20:21], v[16:17]
	v_pk_mul_f32 v[4:5], v[22:23], v[4:5]
	v_pk_mul_f32 v[18:19], v[24:25], v[18:19]
	v_pk_mul_f32 v[6:7], v[26:27], v[6:7]
	v_pk_mul_f32 v[12:13], v[16:17], v[12:13]
	v_pk_mul_f32 v[8:9], v[4:5], v[8:9]
	v_pk_mul_f32 v[14:15], v[18:19], v[14:15]
	v_pk_mul_f32 v[10:11], v[6:7], v[10:11]
	v_cvt_pk_bf16_f32 v4, v12, v13
	v_cvt_pk_bf16_f32 v5, v8, v9
	v_cvt_pk_bf16_f32 v6, v14, v15
	v_cvt_pk_bf16_f32 v7, v10, v11
	global_store_dwordx4 v[0:1], v[4:7], off
	v_lshl_add_u64 v[0:1], v[0:1], 0, s[12:13]
	v_add_u32_e32 v8, s20, v228
	ds_read_b128 v[8:11], v8 offset:34816
	s_addk_i32 s20, 0x2200
	s_waitcnt lgkmcnt(0)
	v_lshlrev_b32_e32 v12, 16, v8
	v_and_b32_e32 v13, 0xffff0000, v8
	v_lshlrev_b32_e32 v8, 16, v9
	v_and_b32_e32 v9, 0xffff0000, v9
	v_lshlrev_b32_e32 v14, 16, v10
	v_and_b32_e32 v15, 0xffff0000, v10
	v_lshlrev_b32_e32 v10, 16, v11
	v_and_b32_e32 v11, 0xffff0000, v11
	s_waitcnt vmcnt(3)
	v_mov_b32_e32 v4, v40
	v_mov_b32_e32 v5, v41
	v_mov_b32_e32 v6, v42
	v_mov_b32_e32 v7, v43
	v_lshlrev_b32_e32 v16, 16, v4
	v_and_b32_e32 v17, 0xffff0000, v4
	v_lshlrev_b32_e32 v4, 16, v5
	v_and_b32_e32 v5, 0xffff0000, v5
	v_lshlrev_b32_e32 v18, 16, v6
	v_and_b32_e32 v19, 0xffff0000, v6
	v_lshlrev_b32_e32 v6, 16, v7
	v_and_b32_e32 v7, 0xffff0000, v7
	v_mul_f32_e32 v20, 0xbfb8aa3b, v16
	v_mul_f32_e32 v21, 0xbfb8aa3b, v17
	v_mul_f32_e32 v22, 0xbfb8aa3b, v4
	v_mul_f32_e32 v23, 0xbfb8aa3b, v5
	v_mul_f32_e32 v24, 0xbfb8aa3b, v18
	v_mul_f32_e32 v25, 0xbfb8aa3b, v19
	v_mul_f32_e32 v26, 0xbfb8aa3b, v6
	v_mul_f32_e32 v27, 0xbfb8aa3b, v7
	v_exp_f32_e32 v20, v20
	v_exp_f32_e32 v21, v21
	v_exp_f32_e32 v22, v22
	v_exp_f32_e32 v23, v23
	v_exp_f32_e32 v24, v24
	v_exp_f32_e32 v25, v25
	v_exp_f32_e32 v26, v26
	v_exp_f32_e32 v27, v27
	v_add_f32_e32 v20, 1.0, v20
	v_add_f32_e32 v21, 1.0, v21
	v_add_f32_e32 v22, 1.0, v22
	v_add_f32_e32 v23, 1.0, v23
	v_add_f32_e32 v24, 1.0, v24
	v_add_f32_e32 v25, 1.0, v25
	v_add_f32_e32 v26, 1.0, v26
	v_add_f32_e32 v27, 1.0, v27
	v_rcp_f32_e32 v20, v20
	v_rcp_f32_e32 v21, v21
	v_rcp_f32_e32 v22, v22
	v_rcp_f32_e32 v23, v23
	v_rcp_f32_e32 v24, v24
	v_rcp_f32_e32 v25, v25
	v_rcp_f32_e32 v26, v26
	v_rcp_f32_e32 v27, v27
	v_pk_mul_f32 v[16:17], v[20:21], v[16:17]
	v_pk_mul_f32 v[4:5], v[22:23], v[4:5]
	v_pk_mul_f32 v[18:19], v[24:25], v[18:19]
	v_pk_mul_f32 v[6:7], v[26:27], v[6:7]
	v_pk_mul_f32 v[12:13], v[16:17], v[12:13]
	v_pk_mul_f32 v[8:9], v[4:5], v[8:9]
	v_pk_mul_f32 v[14:15], v[18:19], v[14:15]
	v_pk_mul_f32 v[10:11], v[6:7], v[10:11]
	v_cvt_pk_bf16_f32 v4, v12, v13
	v_cvt_pk_bf16_f32 v5, v8, v9
	v_cvt_pk_bf16_f32 v6, v14, v15
	v_cvt_pk_bf16_f32 v7, v10, v11
	global_store_dwordx4 v[0:1], v[4:7], off
	v_lshl_add_u64 v[0:1], v[0:1], 0, s[12:13]
	v_readfirstlane_b32 s35, v253
	s_bfe_u32 s39, s35, 0x20006
	s_barrier
; #define ATT_LOAD(t) do { _Pragma("unroll") for (int j = 0; j < 3; ++j) { const int id = tid + 512 * j; const int ch = id % 24; kreg[j] = *(const u32x4*)(ksrc[j] + (size_t)(t) * (ch < 16 ? kstep_n : kstep_p)); } \
;         _Pragma("unroll") for (int j = 0; j < 2; ++j) vreg[j] = *(const u32x4*)(vsrc[j] + (size_t)(t) * 8192); } while (0)
; #define ATT_STORE(buf) do { LAS unsigned char* kb_ = lds + (buf) * ATT_STAGE; LAS unsigned char* vb_ = kb_ + KBUF_B; \
;         _Pragma("unroll") for (int j = 0; j < 3; ++j) *(LAS u32x4*)(kb_ + kdst[j]) = kreg[j]; \
;         _Pragma("unroll") for (int j = 0; j < 2; ++j) *(LAS u32x4*)(vb_ + vdst[j]) = vreg[j]; } while (0)
; DI void attn_item(LAS unsigned char* lds, int bh, int qb, const bf16_t* QH, const bf16_t* KN, const bf16_t* KPE, const bf16_t* VT, const bf16_t* P, bf16_t* MIX) {
;     ...
;     const bf16_t* ksrc[3]; int kdst[3];
; #pragma unroll
;     for (int j = 0; j < 3; ++j) { const int id = tid + 512 * j, key = id / 24, ch = id - key * 24;
;         ksrc[j] = ch < 16 ? KN + ((size_t)bh * SEQ + key) * 128 + ch * 8 : KPE + ((size_t)b * SEQ + key) * 64 + (ch - 16) * 8;
;         kdst[j] = key * KROW + ch * 16; }
;     const bf16_t* vsrc[2]; int vdst[2];
; #pragma unroll
;     for (int j = 0; j < 2; ++j) { const int id = tid + 512 * j, key = id >> 4, ch = id & 15;
;         vsrc[j] = VT + ((size_t)bh * SEQ + key) * 128 + ch * 8; vdst[j] = key * VROW + ch * 16; }
;     const size_t kstep_n = (size_t)64 * 128, kstep_p = (size_t)64 * 64;
;     u32x4 kreg[3], vreg[2];
;     ...
;     ATT_LOAD(0);
;     bf16x8 Qf[12];
;     { const bf16_t* qp = QH + ((size_t)bh * SEQ + q0 + rg * 32 + r) * 192 + 8 * h2;
; #pragma unroll
;       for (int ks = 0; ks < 12; ++ks) Qf[ks] = *(const bf16x8*)(qp + 16 * ks); }
;     ATT_STORE(0);
;     ATT_LOAD(1);
;     f32x16 O[4];
; #pragma unroll
;     for (int d = 0; d < 4; ++d)
; #pragma unroll
;         for (int i = 0; i < 16; ++i) O[d][i] = 0.f;
;     const float NEG = -1e30f;
;     float mrow = NEG, lrow = 0.f;
;     const int qpos = q0 + rg * 32 + r;
	s_lshl_b32 s41, s34, 7
	global_load_dwordx4 v[16:19], v[190:191], off
	global_load_dwordx4 v[20:23], v[192:193], off
	global_load_dwordx4 v[24:27], v[194:195], off
	global_load_dwordx4 v[28:31], v[200:201], off
	global_load_dwordx4 v[32:35], v[202:203], off
	v_lshl_or_b32 v202, s39, 5, v169
	v_or_b32_e32 v203, s41, v202
	v_or_b32_e32 v0, s18, v203
	v_mad_u64_u32 v[0:1], s[20:21], v0, s28, v[166:167]
	v_mad_i32_i24 v1, s19, v229, v1
	global_load_dwordx4 v[124:127], v[0:1], off
	global_load_dwordx4 v[120:123], v[0:1], off offset:32
	global_load_dwordx4 v[116:119], v[0:1], off offset:64
	global_load_dwordx4 v[112:115], v[0:1], off offset:96
	global_load_dwordx4 v[104:107], v[0:1], off offset:128
	global_load_dwordx4 v[96:99], v[0:1], off offset:160
	global_load_dwordx4 v[92:95], v[0:1], off offset:192
	global_load_dwordx4 v[88:91], v[0:1], off offset:224
	global_load_dwordx4 v[80:83], v[0:1], off offset:256
	global_load_dwordx4 v[84:87], v[0:1], off offset:288
	global_load_dwordx4 v[108:111], v[0:1], off offset:320
	global_load_dwordx4 v[100:103], v[0:1], off offset:352
	global_load_dwordx4 v[128:131], v[204:205], off
	global_load_dwordx4 v[132:135], v[206:207], off
	global_load_dwordx4 v[136:139], v[208:209], off
	global_load_dwordx4 v[140:143], v[210:211], off
	global_load_dwordx4 v[144:147], v[212:213], off
	s_lshr_b32 s40, s35, 8
	s_lshl_b32 s18, s40, 5
	v_or_b32_e32 v15, s18, v169
	v_mov_b32_e32 v14, v149
	v_or_b32_e32 v36, s18, v224
	v_mul_lo_u32 v205, v15, s3
	v_mov_b32_e32 v15, v149
	v_mov_b32_e32 v0, v149
	v_mov_b32_e32 v1, v149
	v_mov_b32_e32 v2, v149
	v_mov_b32_e32 v3, v149
	v_mov_b32_e32 v4, v149
	v_mov_b32_e32 v5, v149
	v_mov_b32_e32 v6, v149
	v_mov_b32_e32 v7, v149
	v_mov_b32_e32 v8, v149
	v_mov_b32_e32 v9, v149
	v_mov_b32_e32 v10, v149
	v_mov_b32_e32 v11, v149
	v_mov_b32_e32 v12, v149
	v_mov_b32_e32 v13, v149
	v_mul_lo_u32 v201, v36, s26
	v_mov_b64_e32 v[62:63], v[14:15]
	s_lshl_b32 s42, s34, 1
	s_mov_b32 s43, 0
	s_or_b32 s44, s41, 64
	v_or_b32_e32 v204, s18, v223
	v_mov_b32_e32 v200, 0xf149f2ca
	s_mov_b64 s[18:19], 2
	v_mov_b64_e32 v[60:61], v[12:13]
	v_mov_b64_e32 v[58:59], v[10:11]
	v_mov_b64_e32 v[56:57], v[8:9]
	v_mov_b64_e32 v[54:55], v[6:7]
	v_mov_b64_e32 v[52:53], v[4:5]
	v_mov_b64_e32 v[50:51], v[2:3]
	v_mov_b64_e32 v[48:49], v[0:1]
	s_waitcnt vmcnt(21)
	ds_write_b128 v183, v[16:19]
	s_waitcnt vmcnt(20)
	ds_write_b128 v185, v[20:23]
	s_waitcnt vmcnt(19)
	ds_write_b128 v187, v[24:27]
	s_waitcnt vmcnt(18)
	ds_write_b128 v189, v[28:31] offset:25600
	s_waitcnt vmcnt(17)
	ds_write_b128 v231, v[32:35] offset:25600
	v_mov_b64_e32 v[30:31], v[14:15]
	v_mov_b64_e32 v[46:47], v[14:15]
	v_mov_b32_e32 v183, 0
	v_mov_b64_e32 v[28:29], v[12:13]
	v_mov_b64_e32 v[26:27], v[10:11]
	v_mov_b64_e32 v[24:25], v[8:9]
	v_mov_b64_e32 v[22:23], v[6:7]
	v_mov_b64_e32 v[20:21], v[4:5]
	v_mov_b64_e32 v[18:19], v[2:3]
	v_mov_b64_e32 v[16:17], v[0:1]
	v_mov_b64_e32 v[44:45], v[12:13]
	v_mov_b64_e32 v[42:43], v[10:11]
	v_mov_b64_e32 v[40:41], v[8:9]
	v_mov_b64_e32 v[38:39], v[6:7]
	v_mov_b64_e32 v[36:37], v[4:5]
	v_mov_b64_e32 v[34:35], v[2:3]
	v_mov_b64_e32 v[32:33], v[0:1]
	s_branch .LBB0_610

; #define LAS __attribute__((address_space(3)))
; DI float siluf_(float x) { return x * frcp(1.f + fexp(-x)); }
; DI u32x4 pack8(const f32x4 a, const f32x4 b) { u32x4 w; w.x = pk2(a[0], a[1]); w.y = pk2(a[2], a[3]); w.z = pk2(b[0], b[1]); w.w = pk2(b[2], b[3]); return w; }
; DI void attn_item(LAS unsigned char* lds, int bh, int qb, const bf16_t* QH, const bf16_t* KN, const bf16_t* KPE, const bf16_t* VT, const bf16_t* P, bf16_t* MIX) {
;     ...
;     __syncthreads();
;     {
;         const bf16_t* zp = P + ((size_t)b * SEQ + q0) * LDP + 4160 + h * 128;
;         bf16_t* op = MIX + ((size_t)b * SEQ + q0) * DM + 1024 + h * 128;
; #pragma nounroll
;         for (int j = 0; j < 4; ++j) {
;             const int id = tid + 512 * j, q = id >> 4, c8 = (id & 15) * 8;
;             const u32x4 ov = *(const LAS u32x4*)(OBa + q * 272 + c8 * 2);
;             const u32x4 z = *(const u32x4*)(zp + (size_t)q * LDP + c8);
;             f32x4 o0, o1;
;             o0[0] = bflo(ov.x) * siluf_(bflo(z.x)); o0[1] = bfhi(ov.x) * siluf_(bfhi(z.x)); o0[2] = bflo(ov.y) * siluf_(bflo(z.y)); o0[3] = bfhi(ov.y) * siluf_(bfhi(z.y));
;             o1[0] = bflo(ov.z) * siluf_(bflo(z.z)); o1[1] = bfhi(ov.z) * siluf_(bfhi(z.z)); o1[2] = bflo(ov.w) * siluf_(bflo(z.w)); o1[3] = bfhi(ov.w) * siluf_(bfhi(z.w));
;             *(u32x4*)(op + (size_t)q * DM + c8) = pack8(o0, o1);
;         }
.LBB0_622:
	s_lshl_b32 s18, s34, 19
	s_add_u32 s18, s22, s18
	s_addc_u32 s19, s23, 0
	s_add_u32 s18, s18, s36
	s_addc_u32 s19, s19, 0
	s_mul_i32 s34, s34, 0x144000
	v_lshl_add_u64 v[0:1], v[178:179], 0, s[18:19]
	s_add_u32 s18, s38, s34
	s_addc_u32 s19, s37, 0
	s_add_u32 s18, s18, s36
	s_addc_u32 s19, s19, 0
	v_lshl_add_u64 v[2:3], v[180:181], 0, s[18:19]
	s_mov_b32 s18, 0xffff7800
	global_load_dwordx4 v[28:31], v[2:3], off
	v_lshl_add_u64 v[2:3], v[2:3], 0, s[16:17]
	global_load_dwordx4 v[32:35], v[2:3], off
	v_lshl_add_u64 v[2:3], v[2:3], 0, s[16:17]
	global_load_dwordx4 v[36:39], v[2:3], off
	v_lshl_add_u64 v[2:3], v[2:3], 0, s[16:17]
	global_load_dwordx4 v[40:43], v[2:3], off
	s_waitcnt lgkmcnt(0)
	s_barrier
	v_add_u32_e32 v8, s18, v228
	ds_read_b128 v[8:11], v8 offset:34816
	s_addk_i32 s18, 0x2200
	s_waitcnt lgkmcnt(0)
	v_lshlrev_b32_e32 v12, 16, v8
	v_and_b32_e32 v13, 0xffff0000, v8
	v_lshlrev_b32_e32 v8, 16, v9
	v_and_b32_e32 v9, 0xffff0000, v9
	v_lshlrev_b32_e32 v14, 16, v10
	v_and_b32_e32 v15, 0xffff0000, v10
	v_lshlrev_b32_e32 v10, 16, v11
	v_and_b32_e32 v11, 0xffff0000, v11
	s_waitcnt vmcnt(3)
	v_mov_b32_e32 v4, v28
	v_mov_b32_e32 v5, v29
	v_mov_b32_e32 v6, v30
	v_mov_b32_e32 v7, v31
	v_lshlrev_b32_e32 v16, 16, v4
	v_and_b32_e32 v17, 0xffff0000, v4
	v_lshlrev_b32_e32 v4, 16, v5
	v_and_b32_e32 v5, 0xffff0000, v5
	v_lshlrev_b32_e32 v18, 16, v6
	v_and_b32_e32 v19, 0xffff0000, v6
	v_lshlrev_b32_e32 v6, 16, v7
	v_and_b32_e32 v7, 0xffff0000, v7
	v_mul_f32_e32 v20, 0xbfb8aa3b, v16
	v_mul_f32_e32 v21, 0xbfb8aa3b, v17
	v_mul_f32_e32 v22, 0xbfb8aa3b, v4
	v_mul_f32_e32 v23, 0xbfb8aa3b, v5
	v_mul_f32_e32 v24, 0xbfb8aa3b, v18
	v_mul_f32_e32 v25, 0xbfb8aa3b, v19
	v_mul_f32_e32 v26, 0xbfb8aa3b, v6
	v_mul_f32_e32 v27, 0xbfb8aa3b, v7
	v_exp_f32_e32 v20, v20
	v_exp_f32_e32 v21, v21
	v_exp_f32_e32 v22, v22
	v_exp_f32_e32 v23, v23
	v_exp_f32_e32 v24, v24
	v_exp_f32_e32 v25, v25
	v_exp_f32_e32 v26, v26
	v_exp_f32_e32 v27, v27
	v_add_f32_e32 v20, 1.0, v20
	v_add_f32_e32 v21, 1.0, v21
	v_add_f32_e32 v22, 1.0, v22
	v_add_f32_e32 v23, 1.0, v23
	v_add_f32_e32 v24, 1.0, v24
	v_add_f32_e32 v25, 1.0, v25
	v_add_f32_e32 v26, 1.0, v26
	v_add_f32_e32 v27, 1.0, v27
	v_rcp_f32_e32 v20, v20
	v_rcp_f32_e32 v21, v21
	v_rcp_f32_e32 v22, v22
	v_rcp_f32_e32 v23, v23
	v_rcp_f32_e32 v24, v24
	v_rcp_f32_e32 v25, v25
	v_rcp_f32_e32 v26, v26
	v_rcp_f32_e32 v27, v27
	v_pk_mul_f32 v[16:17], v[20:21], v[16:17]
	v_pk_mul_f32 v[4:5], v[22:23], v[4:5]
	v_pk_mul_f32 v[18:19], v[24:25], v[18:19]
	v_pk_mul_f32 v[6:7], v[26:27], v[6:7]
	v_pk_mul_f32 v[12:13], v[16:17], v[12:13]
	v_pk_mul_f32 v[8:9], v[4:5], v[8:9]
	v_pk_mul_f32 v[14:15], v[18:19], v[14:15]
	v_pk_mul_f32 v[10:11], v[6:7], v[10:11]
	v_cvt_pk_bf16_f32 v4, v12, v13
	v_cvt_pk_bf16_f32 v5, v8, v9
	v_cvt_pk_bf16_f32 v6, v14, v15
	v_cvt_pk_bf16_f32 v7, v10, v11
	global_store_dwordx4 v[0:1], v[4:7], off
	v_lshl_add_u64 v[0:1], v[0:1], 0, s[12:13]
	v_add_u32_e32 v8, s18, v228
	ds_read_b128 v[8:11], v8 offset:34816
	s_addk_i32 s18, 0x2200
	s_waitcnt lgkmcnt(0)
	v_lshlrev_b32_e32 v12, 16, v8
	v_and_b32_e32 v13, 0xffff0000, v8
	v_lshlrev_b32_e32 v8, 16, v9
	v_and_b32_e32 v9, 0xffff0000, v9
	v_lshlrev_b32_e32 v14, 16, v10
	v_and_b32_e32 v15, 0xffff0000, v10
	v_lshlrev_b32_e32 v10, 16, v11
	v_and_b32_e32 v11, 0xffff0000, v11
	s_waitcnt vmcnt(3)
	v_mov_b32_e32 v4, v32
	v_mov_b32_e32 v5, v33
	v_mov_b32_e32 v6, v34
	v_mov_b32_e32 v7, v35
	v_lshlrev_b32_e32 v16, 16, v4
	v_and_b32_e32 v17, 0xffff0000, v4
	v_lshlrev_b32_e32 v4, 16, v5
	v_and_b32_e32 v5, 0xffff0000, v5
	v_lshlrev_b32_e32 v18, 16, v6
	v_and_b32_e32 v19, 0xffff0000, v6
	v_lshlrev_b32_e32 v6, 16, v7
	v_and_b32_e32 v7, 0xffff0000, v7
	v_mul_f32_e32 v20, 0xbfb8aa3b, v16
	v_mul_f32_e32 v21, 0xbfb8aa3b, v17
	v_mul_f32_e32 v22, 0xbfb8aa3b, v4
	v_mul_f32_e32 v23, 0xbfb8aa3b, v5
	v_mul_f32_e32 v24, 0xbfb8aa3b, v18
	v_mul_f32_e32 v25, 0xbfb8aa3b, v19
	v_mul_f32_e32 v26, 0xbfb8aa3b, v6
	v_mul_f32_e32 v27, 0xbfb8aa3b, v7
	v_exp_f32_e32 v20, v20
	v_exp_f32_e32 v21, v21
	v_exp_f32_e32 v22, v22
	v_exp_f32_e32 v23, v23
	v_exp_f32_e32 v24, v24
	v_exp_f32_e32 v25, v25
	v_exp_f32_e32 v26, v26
	v_exp_f32_e32 v27, v27
	v_add_f32_e32 v20, 1.0, v20
	v_add_f32_e32 v21, 1.0, v21
	v_add_f32_e32 v22, 1.0, v22
	v_add_f32_e32 v23, 1.0, v23
	v_add_f32_e32 v24, 1.0, v24
	v_add_f32_e32 v25, 1.0, v25
	v_add_f32_e32 v26, 1.0, v26
	v_add_f32_e32 v27, 1.0, v27
	v_rcp_f32_e32 v20, v20
	v_rcp_f32_e32 v21, v21
	v_rcp_f32_e32 v22, v22
	v_rcp_f32_e32 v23, v23
	v_rcp_f32_e32 v24, v24
	v_rcp_f32_e32 v25, v25
	v_rcp_f32_e32 v26, v26
	v_rcp_f32_e32 v27, v27
	v_pk_mul_f32 v[16:17], v[20:21], v[16:17]
	v_pk_mul_f32 v[4:5], v[22:23], v[4:5]
	v_pk_mul_f32 v[18:19], v[24:25], v[18:19]
	v_pk_mul_f32 v[6:7], v[26:27], v[6:7]
	v_pk_mul_f32 v[12:13], v[16:17], v[12:13]
	v_pk_mul_f32 v[8:9], v[4:5], v[8:9]
	v_pk_mul_f32 v[14:15], v[18:19], v[14:15]
	v_pk_mul_f32 v[10:11], v[6:7], v[10:11]
	v_cvt_pk_bf16_f32 v4, v12, v13
	v_cvt_pk_bf16_f32 v5, v8, v9
	v_cvt_pk_bf16_f32 v6, v14, v15
	v_cvt_pk_bf16_f32 v7, v10, v11
	global_store_dwordx4 v[0:1], v[4:7], off
	v_lshl_add_u64 v[0:1], v[0:1], 0, s[12:13]
	v_add_u32_e32 v8, s18, v228
	ds_read_b128 v[8:11], v8 offset:34816
	s_addk_i32 s18, 0x2200
	s_waitcnt lgkmcnt(0)
; #define LAS __attribute__((address_space(3)))
; DI float siluf_(float x) { return x * frcp(1.f + fexp(-x)); }
; DI u32x4 pack8(const f32x4 a, const f32x4 b) { u32x4 w; w.x = pk2(a[0], a[1]); w.y = pk2(a[2], a[3]); w.z = pk2(b[0], b[1]); w.w = pk2(b[2], b[3]); return w; }
; DI void attn_item(LAS unsigned char* lds, int bh, int qb, const bf16_t* QH, const bf16_t* KN, const bf16_t* KPE, const bf16_t* VT, const bf16_t* P, bf16_t* MIX) {
;     ...
;         for (int j = 0; j < 4; ++j) {
;             const int id = tid + 512 * j, q = id >> 4, c8 = (id & 15) * 8;
;             const u32x4 ov = *(const LAS u32x4*)(OBa + q * 272 + c8 * 2);
;             const u32x4 z = *(const u32x4*)(zp + (size_t)q * LDP + c8);
;             f32x4 o0, o1;
;             o0[0] = bflo(ov.x) * siluf_(bflo(z.x)); o0[1] = bfhi(ov.x) * siluf_(bfhi(z.x)); o0[2] = bflo(ov.y) * siluf_(bflo(z.y)); o0[3] = bfhi(ov.y) * siluf_(bfhi(z.y));
;             o1[0] = bflo(ov.z) * siluf_(bflo(z.z)); o1[1] = bfhi(ov.z) * siluf_(bfhi(z.z)); o1[2] = bflo(ov.w) * siluf_(bflo(z.w)); o1[3] = bfhi(ov.w) * siluf_(bfhi(z.w));
;             *(u32x4*)(op + (size_t)q * DM + c8) = pack8(o0, o1);
;         }
;     }
;     __syncthreads();
; __global__ void __launch_bounds__(512, 2) fwd_kernel(Args a) {
;     ...
;         for (int p = vcu; p < 256; p += G) {
;             const int bh = p >> 4, i = p & 15;
;             attn_item(lds, bh, 31 - i, (const bf16_t*)(ws + WS_QH), (const bf16_t*)(ws + WS_KN), (const bf16_t*)(ws + WS_KPE), (const bf16_t*)(ws + WS_VT), PB, MIX);
;             attn_item(lds, bh, i, (const bf16_t*)(ws + WS_QH), (const bf16_t*)(ws + WS_KN), (const bf16_t*)(ws + WS_KPE), (const bf16_t*)(ws + WS_VT), PB, MIX);
;         }
	v_lshlrev_b32_e32 v12, 16, v8
	v_and_b32_e32 v13, 0xffff0000, v8
	v_lshlrev_b32_e32 v8, 16, v9
	v_and_b32_e32 v9, 0xffff0000, v9
	v_lshlrev_b32_e32 v14, 16, v10
	v_and_b32_e32 v15, 0xffff0000, v10
	v_lshlrev_b32_e32 v10, 16, v11
	v_and_b32_e32 v11, 0xffff0000, v11
	s_waitcnt vmcnt(3)
	v_mov_b32_e32 v4, v36
	v_mov_b32_e32 v5, v37
	v_mov_b32_e32 v6, v38
	v_mov_b32_e32 v7, v39
	v_lshlrev_b32_e32 v16, 16, v4
	v_and_b32_e32 v17, 0xffff0000, v4
	v_lshlrev_b32_e32 v4, 16, v5
	v_and_b32_e32 v5, 0xffff0000, v5
	v_lshlrev_b32_e32 v18, 16, v6
	v_and_b32_e32 v19, 0xffff0000, v6
	v_lshlrev_b32_e32 v6, 16, v7
	v_and_b32_e32 v7, 0xffff0000, v7
	v_mul_f32_e32 v20, 0xbfb8aa3b, v16
	v_mul_f32_e32 v21, 0xbfb8aa3b, v17
	v_mul_f32_e32 v22, 0xbfb8aa3b, v4
	v_mul_f32_e32 v23, 0xbfb8aa3b, v5
	v_mul_f32_e32 v24, 0xbfb8aa3b, v18
	v_mul_f32_e32 v25, 0xbfb8aa3b, v19
	v_mul_f32_e32 v26, 0xbfb8aa3b, v6
	v_mul_f32_e32 v27, 0xbfb8aa3b, v7
	v_exp_f32_e32 v20, v20
	v_exp_f32_e32 v21, v21
	v_exp_f32_e32 v22, v22
	v_exp_f32_e32 v23, v23
	v_exp_f32_e32 v24, v24
	v_exp_f32_e32 v25, v25
	v_exp_f32_e32 v26, v26
	v_exp_f32_e32 v27, v27
	v_add_f32_e32 v20, 1.0, v20
	v_add_f32_e32 v21, 1.0, v21
	v_add_f32_e32 v22, 1.0, v22
	v_add_f32_e32 v23, 1.0, v23
	v_add_f32_e32 v24, 1.0, v24
	v_add_f32_e32 v25, 1.0, v25
	v_add_f32_e32 v26, 1.0, v26
	v_add_f32_e32 v27, 1.0, v27
	v_rcp_f32_e32 v20, v20
	v_rcp_f32_e32 v21, v21
	v_rcp_f32_e32 v22, v22
	v_rcp_f32_e32 v23, v23
	v_rcp_f32_e32 v24, v24
	v_rcp_f32_e32 v25, v25
	v_rcp_f32_e32 v26, v26
	v_rcp_f32_e32 v27, v27
	v_pk_mul_f32 v[16:17], v[20:21], v[16:17]
	v_pk_mul_f32 v[4:5], v[22:23], v[4:5]
	v_pk_mul_f32 v[18:19], v[24:25], v[18:19]
	v_pk_mul_f32 v[6:7], v[26:27], v[6:7]
	v_pk_mul_f32 v[12:13], v[16:17], v[12:13]
	v_pk_mul_f32 v[8:9], v[4:5], v[8:9]
	v_pk_mul_f32 v[14:15], v[18:19], v[14:15]
	v_pk_mul_f32 v[10:11], v[6:7], v[10:11]
	v_cvt_pk_bf16_f32 v4, v12, v13
	v_cvt_pk_bf16_f32 v5, v8, v9
	v_cvt_pk_bf16_f32 v6, v14, v15
	v_cvt_pk_bf16_f32 v7, v10, v11
	global_store_dwordx4 v[0:1], v[4:7], off
	v_lshl_add_u64 v[0:1], v[0:1], 0, s[12:13]
	v_add_u32_e32 v8, s18, v228
	ds_read_b128 v[8:11], v8 offset:34816
	s_addk_i32 s18, 0x2200
	s_waitcnt lgkmcnt(0)
	v_lshlrev_b32_e32 v12, 16, v8
	v_and_b32_e32 v13, 0xffff0000, v8
	v_lshlrev_b32_e32 v8, 16, v9
	v_and_b32_e32 v9, 0xffff0000, v9
	v_lshlrev_b32_e32 v14, 16, v10
	v_and_b32_e32 v15, 0xffff0000, v10
	v_lshlrev_b32_e32 v10, 16, v11
	v_and_b32_e32 v11, 0xffff0000, v11
	s_waitcnt vmcnt(3)
	v_mov_b32_e32 v4, v40
	v_mov_b32_e32 v5, v41
	v_mov_b32_e32 v6, v42
	v_mov_b32_e32 v7, v43
	v_lshlrev_b32_e32 v16, 16, v4
	v_and_b32_e32 v17, 0xffff0000, v4
	v_lshlrev_b32_e32 v4, 16, v5
	v_and_b32_e32 v5, 0xffff0000, v5
	v_lshlrev_b32_e32 v18, 16, v6
	v_and_b32_e32 v19, 0xffff0000, v6
	v_lshlrev_b32_e32 v6, 16, v7
	v_and_b32_e32 v7, 0xffff0000, v7
	v_mul_f32_e32 v20, 0xbfb8aa3b, v16
	v_mul_f32_e32 v21, 0xbfb8aa3b, v17
	v_mul_f32_e32 v22, 0xbfb8aa3b, v4
	v_mul_f32_e32 v23, 0xbfb8aa3b, v5
	v_mul_f32_e32 v24, 0xbfb8aa3b, v18
	v_mul_f32_e32 v25, 0xbfb8aa3b, v19
	v_mul_f32_e32 v26, 0xbfb8aa3b, v6
	v_mul_f32_e32 v27, 0xbfb8aa3b, v7
	v_exp_f32_e32 v20, v20
	v_exp_f32_e32 v21, v21
	v_exp_f32_e32 v22, v22
	v_exp_f32_e32 v23, v23
	v_exp_f32_e32 v24, v24
	v_exp_f32_e32 v25, v25
	v_exp_f32_e32 v26, v26
	v_exp_f32_e32 v27, v27
	v_add_f32_e32 v20, 1.0, v20
	v_add_f32_e32 v21, 1.0, v21
	v_add_f32_e32 v22, 1.0, v22
	v_add_f32_e32 v23, 1.0, v23
	v_add_f32_e32 v24, 1.0, v24
	v_add_f32_e32 v25, 1.0, v25
	v_add_f32_e32 v26, 1.0, v26
	v_add_f32_e32 v27, 1.0, v27
	v_rcp_f32_e32 v20, v20
	v_rcp_f32_e32 v21, v21
	v_rcp_f32_e32 v22, v22
	v_rcp_f32_e32 v23, v23
	v_rcp_f32_e32 v24, v24
	v_rcp_f32_e32 v25, v25
	v_rcp_f32_e32 v26, v26
	v_rcp_f32_e32 v27, v27
	v_pk_mul_f32 v[16:17], v[20:21], v[16:17]
	v_pk_mul_f32 v[4:5], v[22:23], v[4:5]
	v_pk_mul_f32 v[18:19], v[24:25], v[18:19]
	v_pk_mul_f32 v[6:7], v[26:27], v[6:7]
	v_pk_mul_f32 v[12:13], v[16:17], v[12:13]
	v_pk_mul_f32 v[8:9], v[4:5], v[8:9]
	v_pk_mul_f32 v[14:15], v[18:19], v[14:15]
	v_pk_mul_f32 v[10:11], v[6:7], v[10:11]
	v_cvt_pk_bf16_f32 v4, v12, v13
	v_cvt_pk_bf16_f32 v5, v8, v9
	v_cvt_pk_bf16_f32 v6, v14, v15
	v_cvt_pk_bf16_f32 v7, v10, v11
	global_store_dwordx4 v[0:1], v[4:7], off
	v_lshl_add_u64 v[0:1], v[0:1], 0, s[12:13]
	s_add_i32 s52, s52, s58
	s_cmpk_lt_i32 s52, 0x100
	s_barrier
	s_cbranch_scc1 .LBB0_592

; #define PG8_STAGE(bufoff, gbase, voff) do { _Pragma("unroll") for (int _i = 0; _i < 2; ++_i) \
;         __builtin_amdgcn_global_load_lds((const unsigned*)((const char*)(gbase) + (voff)[_i]), (LAS unsigned*)(lds + (bufoff) + ldsw + _i * 8192), 16, 0, 0); } while (0)
; #define PG8_WAIT_V(n) asm volatile("s_waitcnt vmcnt(" #n ")" ::: "memory")
; template <class Epi, class Sched>
; __device__ __forceinline__ void gemm_phase(LAS unsigned char* lds, const Gemm g, const Sched& S, const Epi& E) {
;     ...
;     for (int i = 0; i < 2; ++i) { int R, C; stage_rc(tid * 16 + i * 8192, R, C); const int Rb = Epi::PERM ? ((R & ~31) + perm32(R & 31)) : R;
;         voffA[i] = (unsigned)(R * g.lda + C) * 2u; voffB[i] = (unsigned)(Rb * g.ldb + C) * 2u; }
;     const size_t kstep = (size_t)(BK * 2);
;     const size_t hsA = (size_t)HALF * g.lda * 2, hsB = (size_t)HALF * g.ldb * 2;
;     const size_t tsA = 2 * hsA, tsB = 2 * hsB;
;     const unsigned ldsw = (unsigned)wid * 1024u;
;     const int aoff = lds_byte(wr * 64 + fr, fq * 8), boff = lds_byte(wc * 32 + fr, fq * 8);
;     ...
;     Unit cur, nxt; int ui = 0;
;     if (!S.next(0, cur)) return;
;     f32x4 acc[2][2][4][2];
; #pragma unroll
;     for (int a = 0; a < 2; ++a)
; #pragma unroll
;         for (int b = 0; b < 2; ++b)
; #pragma unroll
;             for (int m = 0; m < 4; ++m)
; #pragma unroll
;                 for (int n = 0; n < 2; ++n) acc[a][b][m][n] = (f32x4){0.f, 0.f, 0.f, 0.f};
;     bf16x8 At[4][2], B0[2][2], B1[2][2];
;     const char* cA = (const char*)g.A + (size_t)cur.pm * tsA; const char* cB = (const char*)g.Bt + (size_t)cur.pn * tsB;
;     PG8_STAGE(PG8_SB(0, 0), cB, voffB); PG8_STAGE(PG8_SB(0, 1), cB + hsB, voffB); PG8_STAGE(PG8_SA(0, 0), cA, voffA); PG8_STAGE(PG8_SA(0, 1), cA + hsA, voffA);
;     if (wr == 1) PG8_BAR;
;     PG8_WAIT_V(2); PG8_BAR;
;     PG8_STAGE(PG8_SB(1, 0), cB + kstep, voffB); PG8_STAGE(PG8_SA(1, 0), cA + kstep, voffA); PG8_STAGE(PG8_SB(1, 1), cB + hsB + kstep, voffB);
;     DI void operator()(const f32x4 (&acc)[2][2][4][2], const Unit& u, int wr, int wc, int fr, int fq) const {
;     ...
;         for (int i = 0; i < 8; ++i) rsv[i] = ssq8(ssq + (size_t)(rbase + (i >> 2) * 128 + (i & 3) * 16) * 32 + 8 * fq);
; #pragma unroll
;         for (int i = 0; i < 8; ++i) { float sq = rsv[i]; sq += __shfl_xor(sq, 16); sq += __shfl_xor(sq, 32); rsv[i] = rsqrtf(sq * (1.f / 2048.f) + EPS_); }
.LBB0_783:
	s_andn2_b64 vcc, exec, s[4:5]
	s_cbranch_vccnz .LBB0_931
	v_cmp_gt_u32_e32 vcc, 0x100, v253
	s_and_saveexec_b64 s[98:99], vcc
	s_cbranch_execz .Lrt6_skip
	s_lshl_b32 s100, s6, 15
	s_add_u32 s100, s100, s82
	s_addc_u32 s101, s83, 0
	s_add_u32 s100, s100, 0x100000
	s_addc_u32 s101, s101, 0
	v_lshlrev_b32_e32 v0, 7, v253
	global_load_dwordx4 v[4:7], v0, s[100:101]
	global_load_dwordx4 v[8:11], v0, s[100:101] offset:16
	global_load_dwordx4 v[12:15], v0, s[100:101] offset:32
	global_load_dwordx4 v[16:19], v0, s[100:101] offset:48
	global_load_dwordx4 v[20:23], v0, s[100:101] offset:64
	global_load_dwordx4 v[24:27], v0, s[100:101] offset:80
	global_load_dwordx4 v[28:31], v0, s[100:101] offset:96
	global_load_dwordx4 v[32:35], v0, s[100:101] offset:112
	s_waitcnt vmcnt(0)
	v_add_f32_e32 v36, v4, v5
	v_add_f32_e32 v37, v6, v7
	v_add_f32_e32 v36, v36, v37
	v_add_f32_e32 v37, v8, v9
	v_add_f32_e32 v38, v10, v11
	v_add_f32_e32 v37, v37, v38
	v_add_f32_e32 v40, v36, v37
	v_add_f32_e32 v36, v12, v13
	v_add_f32_e32 v37, v14, v15
	v_add_f32_e32 v36, v36, v37
	v_add_f32_e32 v37, v16, v17
	v_add_f32_e32 v38, v18, v19
	v_add_f32_e32 v37, v37, v38
	v_add_f32_e32 v41, v36, v37
	v_add_f32_e32 v36, v20, v21
	v_add_f32_e32 v37, v22, v23
	v_add_f32_e32 v36, v36, v37
	v_add_f32_e32 v37, v24, v25
	v_add_f32_e32 v38, v26, v27
	v_add_f32_e32 v37, v37, v38
	v_add_f32_e32 v42, v36, v37
	v_add_f32_e32 v36, v28, v29
	v_add_f32_e32 v37, v30, v31
	v_add_f32_e32 v36, v36, v37
	v_add_f32_e32 v37, v32, v33
	v_add_f32_e32 v38, v34, v35
	v_add_f32_e32 v37, v37, v38
	v_add_f32_e32 v43, v36, v37
	v_add_f32_e32 v36, v40, v41
	v_add_f32_e32 v37, v42, v43
	v_add_f32_e32 v36, v36, v37
	v_lshlrev_b32_e32 v1, 2, v253
	v_add_u32_e32 v1, 0x20400, v1
	ds_write_b32 v1, v36
.Lrt6_skip:
	s_or_b64 exec, exec, s[98:99]
	s_waitcnt lgkmcnt(0)
	s_barrier
	v_lshrrev_b32_e32 v2, 1, v253
	v_and_b32_e32 v11, 24, v2
	v_lshrrev_b32_e32 v2, 5, v253
	v_and_b32_e32 v2, 4, v2
	v_bfe_u32 v3, v253, 2, 2
	v_lshlrev_b32_e32 v0, 4, v253
	s_waitcnt lgkmcnt(0)
	v_and_b32_e32 v1, 32, v253
	v_bfe_u32 v10, v253, 2, 4
	v_or3_b32 v2, v2, v3, v11
	v_lshrrev_b32_e32 v3, 3, v253
	s_movk_i32 s5, 0x70
	v_bitop3_b32 v8, v0, v1, 48 bitop3:0x6c
	v_and_b32_e32 v9, 64, v253
	v_and_or_b32 v4, v3, s5, v10
	s_movk_i32 s5, 0x60
	v_add_u32_e32 v12, 0x2000, v0
	v_or_b32_e32 v1, v8, v9
	v_and_or_b32 v3, v3, s5, v2
	v_lshrrev_b32_e32 v0, 7, v12
	s_movk_i32 s5, 0xf0
	s_add_u32 s3, s82, 0x2480000
	s_waitcnt vmcnt(0)
	v_lshl_or_b32 v130, v3, 12, v1
	v_and_or_b32 v3, v0, s5, v10
	s_movk_i32 s5, 0xe0
	s_addc_u32 s46, s83, 0
	v_and_or_b32 v0, v0, s5, v2
	s_lshr_b32 s5, s20, 6
	s_ashr_i32 s7, s6, 31
	s_ashr_i32 s9, s8, 31
	s_lshr_b32 s4, s20, 8
	s_lshl_b32 s47, s5, 10
	s_lshl_b64 s[10:11], s[6:7], 20
	s_lshl_b64 s[14:15], s[8:9], 20
	s_add_u32 s40, s3, s14
	s_addc_u32 s41, s46, s15
	s_add_i32 s48, s47, 0
	s_add_i32 m0, s48, 0x10000
	v_lshl_or_b32 v134, v0, 12, v1
	global_load_lds_dwordx4 v130, s[40:41]
	s_add_i32 m0, s48, 0x12000
	s_add_u32 s14, s40, 0x80000
	global_load_lds_dwordx4 v134, s[40:41]
	s_addc_u32 s15, s41, 0
	s_add_i32 m0, s48, 0x14000
	v_lshl_or_b32 v128, v4, 12, v1
	global_load_lds_dwordx4 v130, s[14:15]
	s_add_i32 m0, s48, 0x16000
	s_add_u32 s10, s62, s10
	s_addc_u32 s11, s63, s11
	s_add_i32 s49, s48, 0x2000
	global_load_lds_dwordx4 v134, s[14:15]
	s_mov_b32 m0, s48
	s_add_u32 s14, s10, 0x80000
	v_lshl_or_b32 v132, v3, 12, v1
	global_load_lds_dwordx4 v128, s[10:11]
	s_mov_b32 m0, s49
	s_addc_u32 s15, s11, 0
	s_add_i32 s50, s48, 0x4000
	global_load_lds_dwordx4 v132, s[10:11]
	s_mov_b32 m0, s50
	s_add_i32 s51, s48, 0x6000
	global_load_lds_dwordx4 v128, s[14:15]
	s_mov_b32 m0, s51
	v_mov_b32_e32 v137, 0
	global_load_lds_dwordx4 v132, s[14:15]
	v_mov_b32_e32 v131, v137
	v_mov_b32_e32 v135, v137
	v_mov_b32_e32 v129, v137
	v_mov_b32_e32 v133, v137
	s_cmp_eq_u32 s4, 1
	s_mov_b32 s52, 0
	v_lshl_add_u64 v[6:7], s[40:41], 0, v[130:131]
	v_lshl_add_u64 v[4:5], s[40:41], 0, v[134:135]
	v_lshl_add_u64 v[0:1], s[10:11], 0, v[128:129]
	s_cselect_b64 s[14:15], -1, 0
	s_cmp_lg_u32 s4, 1
	v_lshl_add_u64 v[2:3], s[10:11], 0, v[132:133]
	s_cbranch_scc1 .LBB0_786
	s_barrier

; DI float ssq8(const float* p) { const f32x4 a = *(const f32x4*)p, b = *(const f32x4*)(p + 4); return ((a[0] + a[1]) + (a[2] + a[3])) + ((b[0] + b[1]) + (b[2] + b[3])); }
;     DI void operator()(const f32x4 (&acc)[2][2][4][2], const Unit& u, int wr, int wc, int fr, int fq) const {
;         const int seg = u.pn >> 3, colt = (u.pn & 7) * 256;
;         const size_t dsto = (size_t)(seg == 0) * WS_Q2 + (size_t)(seg == 2) * WS_IV + (size_t)(seg == 3) * WS_G2;
;         bf16_t* dst = (bf16_t*)(ws + dsto);
;         const int rbase = u.pm * 256 + wr * 64 + fr;
;         float rsv[8];
; #pragma unroll
;         for (int i = 0; i < 8; ++i) rsv[i] = ssq8(ssq + (size_t)(rbase + (i >> 2) * 128 + (i & 3) * 16) * 32 + 8 * fq);
.LBB0_799:
	s_ashr_i32 s7, s8, 3
	s_lshl_b32 s9, s8, 8
	s_cmp_lt_u32 s8, 8
	s_cselect_b32 s8, 0x4c80000, 0
	s_cmp_lg_u32 s7, 2
	s_cselect_b64 s[42:43], -1, 0
	s_cmp_eq_u32 s7, 2
	s_cselect_b32 s10, 0xcc80000, 0
	s_add_u32 s8, s82, s8
	s_addc_u32 s11, s83, 0
	s_add_u32 s8, s8, s10
	s_addc_u32 s41, s11, 0
	s_lshl_b32 s35, s6, 8
	s_add_i32 s35, s35, s53
	v_or_b32_e32 v152, s35, v138
	v_ashrrev_i32_e32 v153, 31, v152
	v_lshlrev_b64 v[154:155], 7, v[152:153]
	v_or_b32_e32 v168, 16, v152
	v_lshl_add_u64 v[158:159], v[140:141], 0, v[154:155]
	v_ashrrev_i32_e32 v169, 31, v168
	v_mov_b32_e32 v154, 0
	v_mov_b32_e32 v155, 0
	v_mov_b32_e32 v156, 0
	v_mov_b32_e32 v157, 0
	v_mov_b32_e32 v162, 0
	v_mov_b32_e32 v163, 0
	v_mov_b32_e32 v164, 0
	v_mov_b32_e32 v165, 0
	v_lshlrev_b64 v[158:159], 7, v[168:169]
	v_or_b32_e32 v166, 32, v152
	v_lshl_add_u64 v[158:159], v[140:141], 0, v[158:159]
	v_ashrrev_i32_e32 v167, 31, v166
	v_mov_b32_e32 v170, 0
	v_mov_b32_e32 v171, 0
	v_mov_b32_e32 v172, 0
	v_mov_b32_e32 v173, 0
	v_mov_b32_e32 v174, 0
	v_mov_b32_e32 v175, 0
	v_mov_b32_e32 v176, 0
	v_mov_b32_e32 v177, 0
	v_lshlrev_b64 v[158:159], 7, v[166:167]
	v_or_b32_e32 v160, 48, v152
	v_lshl_add_u64 v[158:159], v[140:141], 0, v[158:159]
	v_ashrrev_i32_e32 v161, 31, v160
	v_mov_b32_e32 v178, 0
	v_mov_b32_e32 v179, 0
	v_mov_b32_e32 v180, 0
	v_mov_b32_e32 v181, 0
	v_mov_b32_e32 v186, 0
	v_mov_b32_e32 v187, 0
	v_mov_b32_e32 v188, 0
	v_mov_b32_e32 v189, 0
	v_lshlrev_b64 v[158:159], 7, v[160:161]
	v_lshl_add_u64 v[158:159], v[140:141], 0, v[158:159]
	v_mov_b32_e32 v190, 0
	v_mov_b32_e32 v191, 0
	v_mov_b32_e32 v192, 0
	v_mov_b32_e32 v193, 0
	v_mov_b32_e32 v194, 0
	v_mov_b32_e32 v195, 0
	v_mov_b32_e32 v196, 0
	v_mov_b32_e32 v197, 0
	v_add_u32_e32 v158, 0x80, v152
	v_ashrrev_i32_e32 v159, 31, v158
	v_lshlrev_b64 v[198:199], 7, v[158:159]
	v_add_u32_e32 v206, 0x90, v152
	v_lshl_add_u64 v[202:203], v[140:141], 0, v[198:199]
	v_ashrrev_i32_e32 v207, 31, v206
	v_mov_b32_e32 v198, 0
	v_mov_b32_e32 v199, 0
	v_mov_b32_e32 v200, 0
	v_mov_b32_e32 v201, 0
	s_nop 0
	v_mov_b32_e32 v202, 0
	v_mov_b32_e32 v203, 0
	v_mov_b32_e32 v204, 0
	v_mov_b32_e32 v205, 0
	v_lshlrev_b64 v[206:207], 7, v[206:207]
	v_add_u32_e32 v214, 0xa0, v152
	v_lshl_add_u64 v[210:211], v[140:141], 0, v[206:207]
	v_ashrrev_i32_e32 v215, 31, v214
	v_mov_b32_e32 v206, 0
	v_mov_b32_e32 v207, 0
	v_mov_b32_e32 v208, 0
	v_mov_b32_e32 v209, 0
	s_nop 0
	v_mov_b32_e32 v210, 0
	v_mov_b32_e32 v211, 0
	v_mov_b32_e32 v212, 0
	v_mov_b32_e32 v213, 0
	v_lshlrev_b64 v[214:215], 7, v[214:215]
	v_lshl_add_u64 v[218:219], v[140:141], 0, v[214:215]
	v_mov_b32_e32 v214, 0
	v_mov_b32_e32 v215, 0
	v_mov_b32_e32 v216, 0
	v_mov_b32_e32 v217, 0
	s_nop 0
	v_mov_b32_e32 v218, 0
	v_mov_b32_e32 v219, 0
	v_mov_b32_e32 v220, 0
	v_mov_b32_e32 v221, 0
	v_add_u32_e32 v222, 0xb0, v152
	v_ashrrev_i32_e32 v223, 31, v222
	v_lshlrev_b64 v[222:223], 7, v[222:223]
	v_lshl_add_u64 v[226:227], v[140:141], 0, v[222:223]
	v_mov_b32_e32 v222, 0
	v_mov_b32_e32 v223, 0
	v_mov_b32_e32 v224, 0
	v_mov_b32_e32 v225, 0
	s_nop 0
	v_mov_b32_e32 v226, 0
	v_mov_b32_e32 v227, 0
	v_mov_b32_e32 v228, 0
	v_mov_b32_e32 v229, 0
	v_and_b32_e32 v230, 0xff, v152
	v_lshlrev_b32_e32 v230, 2, v230
	v_add_u32_e32 v230, 0x20400, v230
	ds_read_b32 v154, v230
	ds_read_b32 v170, v230 offset:64
	ds_read_b32 v178, v230 offset:128
	ds_read_b32 v190, v230 offset:192
	ds_read_b32 v198, v230 offset:512
	ds_read_b32 v206, v230 offset:576
	ds_read_b32 v214, v230 offset:640
	ds_read_b32 v222, v230 offset:704
	s_cmp_eq_u32 s7, 3
	s_cselect_b32 s6, 0x400000, 0
	s_and_b32 s31, s9, 0x700
	s_add_u32 s40, s8, s6
	s_addc_u32 s41, s41, 0
	s_cmp_lg_u32 s7, 1
	s_cselect_b64 s[6:7], -1, 0
	s_mov_b64 s[8:9], -1
	s_waitcnt lgkmcnt(0)
; DI unsigned pkh2(float lo, float hi) { f32x2 v = {lo, hi}; h2_t b = __builtin_convertvector(v, h2_t); return __builtin_bit_cast(unsigned, b); }
; DI u32x4 pack8(const f32x4 a, const f32x4 b) { u32x4 w; w.x = pk2(a[0], a[1]); w.y = pk2(a[2], a[3]); w.z = pk2(b[0], b[1]); w.w = pk2(b[2], b[3]); return w; }
; #define EPI_FENCE() asm volatile("" ::: "memory")
;     DI void operator()(const f32x4 (&acc)[2][2][4][2], const Unit& u, int wr, int wc, int fr, int fq) const {
;     ...
;         for (int i = 0; i < 8; ++i) rsv[i] = ssq8(ssq + (size_t)(rbase + (i >> 2) * 128 + (i & 3) * 16) * 32 + 8 * fq);
; #pragma unroll
;         for (int i = 0; i < 8; ++i) { float sq = rsv[i]; sq += __shfl_xor(sq, 16); sq += __shfl_xor(sq, 32); rsv[i] = rsqrtf(sq * (1.f / 2048.f) + EPS_); }
;         EPI_FENCE();
; #pragma unroll
;         for (int ai = 0; ai < 2; ++ai)
; #pragma unroll
;             for (int m = 0; m < 4; ++m) {
;                 const int r = rbase + ai * 128 + m * 16;
;                 const float rs = rsv[ai * 4 + m];
; #pragma unroll
;                 for (int bj = 0; bj < 2; ++bj) {
;                     const int cc = colt + bj * 128 + wc * 32 + 8 * fq;
;                     const f32x4 v0 = acc[ai][bj][m][0] * rs, v1 = acc[ai][bj][m][1] * rs;
;                     const size_t off = (size_t)r * DM + cc;
;                     if (seg == 2) {
;                         const int bb = r >> 12, tt = r & (SEQ - 1), ch = tt >> 6, sl = tt & 63, hh = cc >> 7, vv0 = cc & 127;
;                         bf16_t* vb = dst + ((size_t)(((bb * 16 + hh) * 64 + ch) * 128 + vv0)) * 64 + sl;
;                         const u32x4 w = pack8(v0, v1);
;                         vb[0 * 64] = (bf16_t)(w.x & 0xffff); vb[1 * 64] = (bf16_t)(w.x >> 16);
;                         vb[2 * 64] = (bf16_t)(w.y & 0xffff); vb[3 * 64] = (bf16_t)(w.y >> 16);
;                         vb[4 * 64] = (bf16_t)(w.z & 0xffff); vb[5 * 64] = (bf16_t)(w.z >> 16);
;                         vb[6 * 64] = (bf16_t)(w.w & 0xffff); vb[7 * 64] = (bf16_t)(w.w >> 16);
;                     } else if (seg == 1) {
;                         u32x4 w; w.x = pkh2(v0[0], v0[1]); w.y = pkh2(v0[2], v0[3]); w.z = pkh2(v1[0], v1[1]); w.w = pkh2(v1[2], v1[3]);
;                         *(u32x4*)(LOGF + off) = w;
;                     } else {
;                         *(u32x4*)(dst + off) = pack8(v0, v1);
	v_and_b32_e32 v231, 48, v252
	v_cmp_eq_u32_e32 vcc, 0, v231
	s_nop 1
	v_cndmask_b32_e32 v154, 0, v154, vcc
	v_cndmask_b32_e32 v170, 0, v170, vcc
	v_cndmask_b32_e32 v178, 0, v178, vcc
	v_cndmask_b32_e32 v190, 0, v190, vcc
	v_cndmask_b32_e32 v198, 0, v198, vcc
	v_cndmask_b32_e32 v206, 0, v206, vcc
	v_cndmask_b32_e32 v214, 0, v214, vcc
	v_cndmask_b32_e32 v222, 0, v222, vcc
	v_mov_b32_e32 v230, v154
	v_mov_b32_e32 v231, v162
	v_mov_b32_e32 v162, v155
	v_mov_b32_e32 v154, v156
	v_mov_b32_e32 v155, v164
	v_mov_b32_e32 v164, v157
	v_pk_add_f32 v[156:157], v[230:231], v[162:163]
	v_pk_add_f32 v[154:155], v[154:155], v[164:165]
	v_mov_b32_e32 v162, v170
	v_mov_b32_e32 v163, v174
	v_mov_b32_e32 v174, v171
	v_mov_b32_e32 v164, v172
	v_mov_b32_e32 v165, v176
	v_mov_b32_e32 v176, v173
	v_mov_b32_e32 v170, v178
	v_mov_b32_e32 v171, v186
	v_mov_b32_e32 v186, v179
	v_mov_b32_e32 v172, v180
	v_mov_b32_e32 v173, v188
	v_mov_b32_e32 v188, v181
	v_mov_b32_e32 v178, v190
	v_mov_b32_e32 v179, v194
	v_mov_b32_e32 v194, v191
	v_mov_b32_e32 v180, v192
	v_mov_b32_e32 v181, v196
	v_mov_b32_e32 v196, v193
	v_pk_add_f32 v[154:155], v[156:157], v[154:155]
	v_pk_add_f32 v[156:157], v[162:163], v[174:175]
	v_pk_add_f32 v[162:163], v[164:165], v[176:177]
	v_pk_add_f32 v[164:165], v[170:171], v[186:187]
	v_pk_add_f32 v[170:171], v[172:173], v[188:189]
	v_pk_add_f32 v[172:173], v[178:179], v[194:195]
	v_pk_add_f32 v[156:157], v[156:157], v[162:163]
	v_pk_add_f32 v[162:163], v[164:165], v[170:171]
	v_pk_add_f32 v[164:165], v[180:181], v[196:197]
	v_mov_b32_e32 v170, v198
	v_pk_add_f32 v[164:165], v[172:173], v[164:165]
	v_mov_b32_e32 v171, v202
	v_mov_b32_e32 v202, v199
	v_mov_b32_e32 v172, v200
	v_mov_b32_e32 v173, v204
	v_mov_b32_e32 v204, v201
	v_pk_add_f32 v[170:171], v[170:171], v[202:203]
	v_pk_add_f32 v[172:173], v[172:173], v[204:205]
	v_and_b32_e32 v174, 64, v185
	v_pk_add_f32 v[176:177], v[170:171], v[172:173]
	v_mov_b32_e32 v170, v206
	v_mov_b32_e32 v171, v210
	v_mov_b32_e32 v210, v207
	v_mov_b32_e32 v172, v208
	v_mov_b32_e32 v173, v212
	v_mov_b32_e32 v212, v209
	v_pk_add_f32 v[170:171], v[170:171], v[210:211]
	v_pk_add_f32 v[172:173], v[172:173], v[212:213]
	v_add_u32_e32 v178, 64, v174
	v_pk_add_f32 v[180:181], v[170:171], v[172:173]
	v_mov_b32_e32 v170, v214
	v_mov_b32_e32 v171, v218
	v_mov_b32_e32 v218, v215
	v_mov_b32_e32 v172, v216
	v_mov_b32_e32 v173, v220
	v_mov_b32_e32 v220, v217
	v_pk_add_f32 v[170:171], v[170:171], v[218:219]
	v_pk_add_f32 v[172:173], v[172:173], v[220:221]
	v_mov_b32_e32 v174, v156
	v_pk_add_f32 v[186:187], v[170:171], v[172:173]
	v_xor_b32_e32 v173, 16, v185
	v_cmp_lt_i32_e32 vcc, v173, v178
	v_mov_b32_e32 v175, v154
	v_mov_b32_e32 v154, v157
	v_cndmask_b32_e32 v173, v185, v173, vcc
	v_lshlrev_b32_e32 v179, 2, v173
	v_pk_add_f32 v[154:155], v[174:175], v[154:155]
	ds_bpermute_b32 v157, v179, v155
	ds_bpermute_b32 v156, v179, v154
	v_xor_b32_e32 v173, 32, v185
	v_cmp_lt_i32_e32 vcc, v173, v178
	v_mov_b32_e32 v170, v222
	v_mov_b32_e32 v171, v226
	v_cndmask_b32_e32 v173, v185, v173, vcc
	v_lshlrev_b32_e32 v190, 2, v173
	s_waitcnt lgkmcnt(0)
	v_pk_add_f32 v[154:155], v[154:155], v[156:157]
	ds_bpermute_b32 v157, v190, v155
	ds_bpermute_b32 v156, v190, v154
	v_mov_b32_e32 v226, v223
	v_mov_b32_e32 v172, v224
	v_mov_b32_e32 v173, v228
	v_mov_b32_e32 v228, v225
	s_waitcnt lgkmcnt(0)
	v_pk_add_f32 v[154:155], v[154:155], v[156:157]
	v_pk_add_f32 v[170:171], v[170:171], v[226:227]
	v_pk_fma_f32 v[174:175], v[154:155], s[0:1], v[150:151] op_sel_hi:[1,0,0]
	v_pk_add_f32 v[172:173], v[172:173], v[228:229]
	v_mul_f32_e32 v154, 0x4b800000, v175
	v_cmp_gt_f32_e32 vcc, s68, v175
	v_pk_add_f32 v[188:189], v[170:171], v[172:173]
	v_mov_b32_e32 v155, v162
	v_cndmask_b32_e32 v154, v175, v154, vcc
	v_rsq_f32_e32 v170, v154
	v_mov_b32_e32 v154, v164
	v_mov_b32_e32 v162, v165
	v_pk_add_f32 v[154:155], v[154:155], v[162:163]
	ds_bpermute_b32 v157, v179, v155
	ds_bpermute_b32 v156, v179, v154
	v_mul_f32_e32 v162, 0x45800000, v170
	v_cndmask_b32_e32 v178, v170, v162, vcc
	v_mov_b32_e32 v162, v188
	v_mov_b32_e32 v163, v186
	s_waitcnt lgkmcnt(0)
	v_pk_add_f32 v[170:171], v[154:155], v[156:157]
	v_mov_b32_e32 v154, v180
	v_mov_b32_e32 v155, v176
	v_mov_b32_e32 v176, v181
	v_mov_b32_e32 v186, v189
	v_pk_add_f32 v[154:155], v[154:155], v[176:177]
	v_pk_add_f32 v[176:177], v[162:163], v[186:187]
	ds_bpermute_b32 v157, v179, v155
	ds_bpermute_b32 v156, v179, v154
	ds_bpermute_b32 v181, v179, v177
	ds_bpermute_b32 v180, v179, v176
	ds_bpermute_b32 v173, v190, v171
	ds_bpermute_b32 v172, v190, v170
	s_waitcnt lgkmcnt(4)
	v_pk_add_f32 v[162:163], v[154:155], v[156:157]
	ds_bpermute_b32 v165, v190, v163
	s_waitcnt lgkmcnt(3)
	v_pk_add_f32 v[154:155], v[176:177], v[180:181]
	ds_bpermute_b32 v164, v190, v162
	ds_bpermute_b32 v157, v190, v155
	ds_bpermute_b32 v156, v190, v154
	v_cmp_gt_f32_e64 s[10:11], s68, v174
	v_lshlrev_b64 v[176:177], 11, v[152:153]
	v_or_b32_e32 v175, s31, v151
	v_pk_mul_f32 v[126:127], v[126:127], v[178:179] op_sel_hi:[1,0]
	v_pk_mul_f32 v[124:125], v[124:125], v[178:179] op_sel_hi:[1,0]
	v_pk_mul_f32 v[122:123], v[122:123], v[178:179] op_sel_hi:[1,0]
	v_pk_mul_f32 v[180:181], v[120:121], v[178:179] op_sel_hi:[1,0]
	s_and_b64 vcc, exec, s[42:43]
	s_cbranch_vccz .LBB0_805
	v_or_b32_e32 v120, v176, v175
	v_mov_b32_e32 v121, v177
	s_and_b64 vcc, exec, s[6:7]
	s_cbranch_vccz .LBB0_802
	v_cvt_pk_bf16_f32 v186, v124, v125
	v_cvt_pk_bf16_f32 v187, v126, v127
	v_cvt_pk_bf16_f32 v188, v180, v181
	v_cvt_pk_bf16_f32 v189, v122, v123
	v_lshl_add_u64 v[190:191], v[120:121], 1, s[40:41]
	global_store_dwordx4 v[190:191], v[186:189], off
	s_mov_b64 s[8:9], 0

; __global__ void __launch_bounds__(512, 2) fwd_kernel(Args a) {
	.amdhsa_kernel _Z10fwd_kernel4Args
		.amdhsa_group_segment_fixed_size 0
		.amdhsa_private_segment_fixed_size 0
		.amdhsa_kernarg_size 432
		.amdhsa_user_sgpr_count 2
		.amdhsa_user_sgpr_dispatch_ptr 0
		.amdhsa_user_sgpr_queue_ptr 0
		.amdhsa_user_sgpr_kernarg_segment_ptr 1
		.amdhsa_user_sgpr_dispatch_id 0
		.amdhsa_user_sgpr_kernarg_preload_length 0
		.amdhsa_user_sgpr_kernarg_preload_offset 0
		.amdhsa_user_sgpr_private_segment_size 0
		.amdhsa_uses_dynamic_stack 0
		.amdhsa_enable_private_segment 0
		.amdhsa_system_sgpr_workgroup_id_x 1
		.amdhsa_system_sgpr_workgroup_id_y 0
		.amdhsa_system_sgpr_workgroup_id_z 0
		.amdhsa_system_sgpr_workgroup_info 0
		.amdhsa_system_vgpr_workitem_id 2
		.amdhsa_next_free_vgpr 255
		.amdhsa_next_free_sgpr 102
		.amdhsa_accum_offset 256
		.amdhsa_reserve_vcc 1
		.amdhsa_float_round_mode_32 0
		.amdhsa_float_round_mode_16_64 0
		.amdhsa_float_denorm_mode_32 3
		.amdhsa_float_denorm_mode_16_64 3
		.amdhsa_dx10_clamp 1
		.amdhsa_ieee_mode 1
		.amdhsa_fp16_overflow 0
		.amdhsa_tg_split 0
		.amdhsa_exception_fp_ieee_invalid_op 0
		.amdhsa_exception_fp_denorm_src 0
		.amdhsa_exception_fp_ieee_div_zero 0
		.amdhsa_exception_fp_ieee_overflow 0
		.amdhsa_exception_fp_ieee_underflow 0
		.amdhsa_exception_fp_ieee_inexact 0
		.amdhsa_exception_int_div_zero 0
	.end_amdhsa_kernel

; __global__ void __launch_bounds__(512, 2) fwd_kernel(Args a) {
amdhsa.kernels:
  - .agpr_count:     0
    .args:
      - .offset:         0
        .size:           176
        .value_kind:     by_value
      - .offset:         176
        .size:           4
        .value_kind:     hidden_block_count_x
      - .offset:         180
        .size:           4
        .value_kind:     hidden_block_count_y
      - .offset:         184
        .size:           4
        .value_kind:     hidden_block_count_z
      - .offset:         188
        .size:           2
        .value_kind:     hidden_group_size_x
      - .offset:         190
        .size:           2
        .value_kind:     hidden_group_size_y
      - .offset:         192
        .size:           2
        .value_kind:     hidden_group_size_z
      - .offset:         194
        .size:           2
        .value_kind:     hidden_remainder_x
      - .offset:         196
        .size:           2
        .value_kind:     hidden_remainder_y
      - .offset:         198
        .size:           2
        .value_kind:     hidden_remainder_z
      - .offset:         216
        .size:           8
        .value_kind:     hidden_global_offset_x
      - .offset:         224
        .size:           8
        .value_kind:     hidden_global_offset_y
      - .offset:         232
        .size:           8
        .value_kind:     hidden_global_offset_z
      - .offset:         240
        .size:           2
        .value_kind:     hidden_grid_dims
      - .offset:         264
        .size:           8
        .value_kind:     hidden_multigrid_sync_arg
      - .offset:         296
        .size:           4
        .value_kind:     hidden_dynamic_lds_size
    .group_segment_fixed_size: 0
    .kernarg_segment_align: 8
    .kernarg_segment_size: 432
    .language:       OpenCL C
    .language_version:
      - 2
      - 0
    .max_flat_workgroup_size: 512
    .name:           _Z10fwd_kernel4Args
    .private_segment_fixed_size: 0
    .sgpr_count:     108
    .sgpr_spill_count: 4
    .symbol:         _Z10fwd_kernel4Args.kd
    .uniform_work_group_size: 1
    .uses_dynamic_stack: false
    .vgpr_count:     255
    .vgpr_spill_count: 0
    .wavefront_size: 64
